# GEMM loop: fragment ds_reads issued first in each memory cluster (ahead of scalar address arithmetic); m0 writes moved ahead of adds
# baseline (speedup 1.0000x reference)
; #define PG8_STAGE(bufoff, gbase, voff) do { _Pragma("unroll") for (int _i = 0; _i < 2; ++_i) \
;         __builtin_amdgcn_global_load_lds((const unsigned*)((const char*)(gbase) + (voff)[_i]), (LAS unsigned*)(lds + (bufoff) + ldsw + _i * 8192), 16, 0, 0); } while (0)
; #define PG8_LDA(dst, b, h) do { _Pragma("unroll") for (int m = 0; m < 4; ++m) _Pragma("unroll") for (int k = 0; k < 2; ++k) dst[m][k] = *(const LAS h16x8*)(lds + PG8_SA(b, h) + aoff + m * 2048 + k * 1024); } while (0)
; #define PG8_LDB(dst, b, h) do { _Pragma("unroll") for (int n = 0; n < 2; ++n) _Pragma("unroll") for (int k = 0; k < 2; ++k) dst[n][k] = *(const LAS h16x8*)(lds + PG8_SB(b, h) + boff + n * 2048 + k * 1024); } while (0)
; #define PG8_MMA(ai, bj, At, Bt) do { __builtin_amdgcn_s_setprio(1); _Pragma("unroll") for (int m = 0; m < 4; ++m) _Pragma("unroll") for (int n = 0; n < 2; ++n) _Pragma("unroll") for (int k = 0; k < 2; ++k) \
;         acc[ai][bj][m][n] = __builtin_amdgcn_mfma_f32_16x16x32_f16(Bt[n][k], At[m][k], acc[ai][bj][m][n], 0, 0, 0); __builtin_amdgcn_s_setprio(0); } while (0)
; #define PG8_WAIT_V(n) asm volatile("s_waitcnt vmcnt(" #n ")" ::: "memory")
; #define PG8_WAIT_L(n) asm volatile("s_waitcnt lgkmcnt(" #n ")" ::: "memory")
; #define PG8_BAR __builtin_amdgcn_s_barrier()
; #define PG8_SCHED __builtin_amdgcn_sched_barrier(0)
; __device__ __forceinline__ void gemm_phase(LAS unsigned char* lds, const Gemm g, const StaticOrder& S, const Epi& E) {
;     ...
;             PG8_LDB(B0, 0, 0); PG8_SCHED; PG8_LDA(At, 0, 0); PG8_STAGE(PG8_SA(1, 1), a1 + hstepA, voffA);
;             PG8_WAIT_L(8); PG8_BAR; PG8_WAIT_L(0); PG8_MMA(0, 0, At, B0); PG8_BAR; PG8_SCHED;
;             PG8_LDB(B1, 0, 1); PG8_STAGE(PG8_SB(0, 0), b2, voffB);
;             PG8_BAR; PG8_WAIT_L(0); PG8_MMA(0, 1, At, B1); PG8_BAR;
;             PG8_LDA(At, 0, 1); PG8_STAGE(PG8_SA(0, 0), a2, voffA);
;             PG8_BAR; PG8_WAIT_L(0); PG8_MMA(1, 0, At, B0); PG8_BAR; PG8_SCHED;
;             PG8_STAGE(PG8_SB(0, 1), b2 + hstepB, voffB);
;             PG8_WAIT_V(6); PG8_BAR; PG8_MMA(1, 1, At, B1); PG8_BAR;
.Lprio_skip:
.LBB0_762:
	ds_read_b128 v[128:131], v224
	ds_read_b128 v[132:135], v224 offset:1024
	ds_read_b128 v[136:139], v224 offset:2048
	ds_read_b128 v[140:143], v224 offset:3072
	ds_read_b128 v[144:147], v239
	ds_read_b128 v[148:151], v239 offset:1024
	ds_read_b128 v[152:155], v239 offset:2048
	ds_read_b128 v[156:159], v239 offset:3072
	ds_read_b128 v[160:163], v239 offset:4096
	ds_read_b128 v[164:167], v239 offset:5120
	ds_read_b128 v[168:171], v239 offset:6144
	ds_read_b128 v[172:175], v239 offset:7168
	s_cmp_gt_u32 s34, 15
	s_cselect_b64 s[36:37], -1, 0
	s_and_b64 s[36:37], s[6:7], s[36:37]
	s_and_b64 s[36:37], s[36:37], exec
	s_cselect_b32 s42, 0xfffff000, 0
	s_cselect_b32 s43, -1, 0
	s_add_i32 s38, s34, 2
	s_cmp_gt_u32 s34, 13
	s_cselect_b64 s[36:37], -1, 0
	s_and_b64 s[36:37], s[6:7], s[36:37]
	s_and_b64 s[36:37], s[36:37], exec
	s_cselect_b32 s36, 0xfffff000, 0
	s_cselect_b32 s35, -1, 0
	s_add_u32 s36, s0, s36
	s_addc_u32 s35, s1, s35
	s_add_u32 s36, s36, 0x80
	s_addc_u32 s35, s35, 0
	s_cmp_eq_u32 s66, s34
	s_cselect_b32 s34, s4, s36
	s_cselect_b32 s35, s5, s35
	s_cselect_b32 s37, s29, s33
	s_cselect_b32 s36, s28, s27
	s_add_i32 m0, s58, 0xc000
	s_add_u32 s86, s0, s42
	s_addc_u32 s87, s1, s43
	global_load_lds_dwordx4 v212, s[86:87]
	s_add_i32 m0, s58, 0xe000
	s_nop 0
	global_load_lds_dwordx4 v214, s[86:87]
	s_waitcnt lgkmcnt(8)
	s_barrier
	s_waitcnt lgkmcnt(0)
	s_waitcnt lgkmcnt(0)
	v_mfma_f32_16x16x32_f16 v[124:127], v[128:131], v[144:147], v[124:127]
	v_mfma_f32_16x16x32_f16 v[120:123], v[136:139], v[144:147], v[120:123]
	v_mfma_f32_16x16x32_f16 v[108:111], v[128:131], v[152:155], v[108:111]
	v_mfma_f32_16x16x32_f16 v[104:107], v[136:139], v[152:155], v[104:107]
	v_mfma_f32_16x16x32_f16 v[92:95], v[128:131], v[160:163], v[92:95]
	v_mfma_f32_16x16x32_f16 v[88:91], v[136:139], v[160:163], v[88:91]
	v_mfma_f32_16x16x32_f16 v[76:79], v[128:131], v[168:171], v[76:79]
	v_mfma_f32_16x16x32_f16 v[72:75], v[136:139], v[168:171], v[72:75]
	v_mfma_f32_16x16x32_f16 v[124:127], v[132:135], v[148:151], v[124:127]
	v_mfma_f32_16x16x32_f16 v[120:123], v[140:143], v[148:151], v[120:123]
	v_mfma_f32_16x16x32_f16 v[108:111], v[132:135], v[156:159], v[108:111]
	v_mfma_f32_16x16x32_f16 v[104:107], v[140:143], v[156:159], v[104:107]
	v_mfma_f32_16x16x32_f16 v[92:95], v[132:135], v[164:167], v[92:95]
	v_mfma_f32_16x16x32_f16 v[88:91], v[140:143], v[164:167], v[88:91]
	v_mfma_f32_16x16x32_f16 v[76:79], v[132:135], v[172:175], v[76:79]
	v_mfma_f32_16x16x32_f16 v[72:75], v[140:143], v[172:175], v[72:75]
	s_barrier
	ds_read_b128 v[176:179], v225
	ds_read_b128 v[180:183], v225 offset:1024
	ds_read_b128 v[184:187], v225 offset:2048
	ds_read_b128 v[188:191], v225 offset:3072
	s_add_i32 m0, s31, 0x10000
	s_add_u32 s86, s36, 0x80
	s_addc_u32 s87, s37, 0
	global_load_lds_dwordx4 v206, s[36:37]
	s_add_i32 m0, s31, 0x12000
	s_nop 0
	global_load_lds_dwordx4 v210, s[36:37]
	s_barrier
	s_waitcnt lgkmcnt(0)
	s_waitcnt lgkmcnt(0)
	v_mfma_f32_16x16x32_f16 v[116:119], v[176:179], v[144:147], v[116:119]
	v_mfma_f32_16x16x32_f16 v[112:115], v[184:187], v[144:147], v[112:115]
	v_mfma_f32_16x16x32_f16 v[100:103], v[176:179], v[152:155], v[100:103]
	v_mfma_f32_16x16x32_f16 v[96:99], v[184:187], v[152:155], v[96:99]
	v_mfma_f32_16x16x32_f16 v[84:87], v[176:179], v[160:163], v[84:87]
	v_mfma_f32_16x16x32_f16 v[80:83], v[184:187], v[160:163], v[80:83]
	v_mfma_f32_16x16x32_f16 v[68:71], v[176:179], v[168:171], v[68:71]
	v_mfma_f32_16x16x32_f16 v[64:67], v[184:187], v[168:171], v[64:67]
	v_mfma_f32_16x16x32_f16 v[116:119], v[180:183], v[148:151], v[116:119]
	v_mfma_f32_16x16x32_f16 v[112:115], v[188:191], v[148:151], v[112:115]
	v_mfma_f32_16x16x32_f16 v[100:103], v[180:183], v[156:159], v[100:103]
	v_mfma_f32_16x16x32_f16 v[96:99], v[188:191], v[156:159], v[96:99]
	v_mfma_f32_16x16x32_f16 v[84:87], v[180:183], v[164:167], v[84:87]
	v_mfma_f32_16x16x32_f16 v[80:83], v[188:191], v[164:167], v[80:83]
	v_mfma_f32_16x16x32_f16 v[68:71], v[180:183], v[172:175], v[68:71]
	v_mfma_f32_16x16x32_f16 v[64:67], v[188:191], v[172:175], v[64:67]
	s_mov_b32 m0, s58
	s_add_u32 s88, s34, 0x80
	s_addc_u32 s89, s35, 0
	s_barrier
	ds_read_b128 v[144:147], v239 offset:16384
	ds_read_b128 v[148:151], v239 offset:17408
	ds_read_b128 v[152:155], v239 offset:18432
	ds_read_b128 v[156:159], v239 offset:19456
	ds_read_b128 v[160:163], v239 offset:20480
	ds_read_b128 v[164:167], v239 offset:21504
	ds_read_b128 v[168:171], v239 offset:22528
	ds_read_b128 v[172:175], v239 offset:23552
	global_load_lds_dwordx4 v204, s[34:35]
	s_mov_b32 m0, s59
	s_nop 0
	global_load_lds_dwordx4 v208, s[34:35]
	s_barrier
	s_waitcnt lgkmcnt(0)
	s_waitcnt lgkmcnt(0)
	v_mfma_f32_16x16x32_f16 v[60:63], v[128:131], v[144:147], v[60:63]
	v_mfma_f32_16x16x32_f16 v[56:59], v[136:139], v[144:147], v[56:59]
	v_mfma_f32_16x16x32_f16 v[44:47], v[128:131], v[152:155], v[44:47]
	v_mfma_f32_16x16x32_f16 v[40:43], v[136:139], v[152:155], v[40:43]
	v_mfma_f32_16x16x32_f16 v[28:31], v[128:131], v[160:163], v[28:31]
	v_mfma_f32_16x16x32_f16 v[24:27], v[136:139], v[160:163], v[24:27]
	v_mfma_f32_16x16x32_f16 v[12:15], v[128:131], v[168:171], v[12:15]
	v_mfma_f32_16x16x32_f16 v[8:11], v[136:139], v[168:171], v[8:11]
	v_mfma_f32_16x16x32_f16 v[60:63], v[132:135], v[148:151], v[60:63]
	v_mfma_f32_16x16x32_f16 v[56:59], v[140:143], v[148:151], v[56:59]
	v_mfma_f32_16x16x32_f16 v[44:47], v[132:135], v[156:159], v[44:47]
	v_mfma_f32_16x16x32_f16 v[40:43], v[140:143], v[156:159], v[40:43]
	v_mfma_f32_16x16x32_f16 v[28:31], v[132:135], v[164:167], v[28:31]
	v_mfma_f32_16x16x32_f16 v[24:27], v[140:143], v[164:167], v[24:27]
	v_mfma_f32_16x16x32_f16 v[12:15], v[132:135], v[172:175], v[12:15]
	v_mfma_f32_16x16x32_f16 v[8:11], v[140:143], v[172:175], v[8:11]
	s_barrier
; #define PG8_STAGE(bufoff, gbase, voff) do { _Pragma("unroll") for (int _i = 0; _i < 2; ++_i) \
;         __builtin_amdgcn_global_load_lds((const unsigned*)((const char*)(gbase) + (voff)[_i]), (LAS unsigned*)(lds + (bufoff) + ldsw + _i * 8192), 16, 0, 0); } while (0)
; #define PG8_LDA(dst, b, h) do { _Pragma("unroll") for (int m = 0; m < 4; ++m) _Pragma("unroll") for (int k = 0; k < 2; ++k) dst[m][k] = *(const LAS h16x8*)(lds + PG8_SA(b, h) + aoff + m * 2048 + k * 1024); } while (0)
; #define PG8_LDB(dst, b, h) do { _Pragma("unroll") for (int n = 0; n < 2; ++n) _Pragma("unroll") for (int k = 0; k < 2; ++k) dst[n][k] = *(const LAS h16x8*)(lds + PG8_SB(b, h) + boff + n * 2048 + k * 1024); } while (0)
; #define PG8_MMA(ai, bj, At, Bt) do { __builtin_amdgcn_s_setprio(1); _Pragma("unroll") for (int m = 0; m < 4; ++m) _Pragma("unroll") for (int n = 0; n < 2; ++n) _Pragma("unroll") for (int k = 0; k < 2; ++k) \
;         acc[ai][bj][m][n] = __builtin_amdgcn_mfma_f32_16x16x32_f16(Bt[n][k], At[m][k], acc[ai][bj][m][n], 0, 0, 0); __builtin_amdgcn_s_setprio(0); } while (0)
; #define PG8_WAIT_V(n) asm volatile("s_waitcnt vmcnt(" #n ")" ::: "memory")
; #define PG8_WAIT_L(n) asm volatile("s_waitcnt lgkmcnt(" #n ")" ::: "memory")
; #define PG8_BAR __builtin_amdgcn_s_barrier()
; #define PG8_SCHED __builtin_amdgcn_sched_barrier(0)
; __device__ __forceinline__ void gemm_phase(LAS unsigned char* lds, const Gemm g, const StaticOrder& S, const Epi& E) {
;     ...
;             PG8_WAIT_V(6); PG8_BAR; PG8_MMA(1, 1, At, B1); PG8_BAR;
;             PG8_LDB(B0, 1, 0); PG8_SCHED; PG8_LDA(At, 1, 0); PG8_STAGE(PG8_SA(0, 1), a2 + hstepA, voffA);
;             PG8_WAIT_L(8); PG8_BAR; PG8_WAIT_L(0); PG8_MMA(0, 0, At, B0); PG8_BAR; PG8_SCHED;
;             PG8_LDB(B1, 1, 1); PG8_STAGE(PG8_SB(1, 0), b3, voffB);
;             PG8_BAR; PG8_WAIT_L(0); PG8_MMA(0, 1, At, B1); PG8_BAR;
;             PG8_LDA(At, 1, 1); PG8_STAGE(PG8_SA(1, 0), a3, voffA);
	s_add_u32 s36, s36, s18
	s_addc_u32 s37, s37, s19
	s_add_u32 s96, s36, 0x80
	s_addc_u32 s97, s37, 0
	s_add_i32 m0, s31, 0x14000
	s_nop 0
	global_load_lds_dwordx4 v206, s[36:37]
	s_add_i32 m0, s31, 0x16000
	s_nop 0
	global_load_lds_dwordx4 v210, s[36:37]
	s_waitcnt vmcnt(6)
	s_barrier
	v_mfma_f32_16x16x32_f16 v[52:55], v[176:179], v[144:147], v[52:55]
	v_mfma_f32_16x16x32_f16 v[48:51], v[184:187], v[144:147], v[48:51]
	v_mfma_f32_16x16x32_f16 v[36:39], v[176:179], v[152:155], v[36:39]
	v_mfma_f32_16x16x32_f16 v[32:35], v[184:187], v[152:155], v[32:35]
	v_mfma_f32_16x16x32_f16 v[20:23], v[176:179], v[160:163], v[20:23]
	v_mfma_f32_16x16x32_f16 v[16:19], v[184:187], v[160:163], v[16:19]
	v_mfma_f32_16x16x32_f16 v[4:7], v[176:179], v[168:171], v[4:7]
	v_mfma_f32_16x16x32_f16 v[0:3], v[184:187], v[168:171], v[0:3]
	v_mfma_f32_16x16x32_f16 v[52:55], v[180:183], v[148:151], v[52:55]
	v_mfma_f32_16x16x32_f16 v[48:51], v[188:191], v[148:151], v[48:51]
	v_mfma_f32_16x16x32_f16 v[36:39], v[180:183], v[156:159], v[36:39]
	v_mfma_f32_16x16x32_f16 v[32:35], v[188:191], v[156:159], v[32:35]
	v_mfma_f32_16x16x32_f16 v[20:23], v[180:183], v[164:167], v[20:23]
	v_mfma_f32_16x16x32_f16 v[16:19], v[188:191], v[164:167], v[16:19]
	v_mfma_f32_16x16x32_f16 v[4:7], v[180:183], v[172:175], v[4:7]
	v_mfma_f32_16x16x32_f16 v[0:3], v[188:191], v[172:175], v[0:3]
	s_barrier
	ds_read_b128 v[128:131], v241
	ds_read_b128 v[132:135], v241 offset:1024
	ds_read_b128 v[136:139], v241 offset:2048
	ds_read_b128 v[140:143], v241 offset:3072
	ds_read_b128 v[144:147], v239 offset:32768
	ds_read_b128 v[148:151], v239 offset:33792
	ds_read_b128 v[152:155], v239 offset:34816
	ds_read_b128 v[156:159], v239 offset:35840
	ds_read_b128 v[160:163], v239 offset:36864
	ds_read_b128 v[164:167], v239 offset:37888
	ds_read_b128 v[168:171], v239 offset:38912
	ds_read_b128 v[172:175], v239 offset:39936
	s_mov_b32 m0, s60
	s_add_u32 s34, s34, s16
	s_addc_u32 s35, s35, s17
	global_load_lds_dwordx4 v204, s[34:35]
	s_mov_b32 m0, s61
	s_nop 0
	global_load_lds_dwordx4 v208, s[34:35]
	s_waitcnt lgkmcnt(8)
	s_barrier
	s_waitcnt lgkmcnt(0)
	s_waitcnt lgkmcnt(0)
	v_mfma_f32_16x16x32_f16 v[124:127], v[128:131], v[144:147], v[124:127]
	v_mfma_f32_16x16x32_f16 v[120:123], v[136:139], v[144:147], v[120:123]
	v_mfma_f32_16x16x32_f16 v[108:111], v[128:131], v[152:155], v[108:111]
	v_mfma_f32_16x16x32_f16 v[104:107], v[136:139], v[152:155], v[104:107]
	v_mfma_f32_16x16x32_f16 v[92:95], v[128:131], v[160:163], v[92:95]
	v_mfma_f32_16x16x32_f16 v[88:91], v[136:139], v[160:163], v[88:91]
	v_mfma_f32_16x16x32_f16 v[76:79], v[128:131], v[168:171], v[76:79]
	v_mfma_f32_16x16x32_f16 v[72:75], v[136:139], v[168:171], v[72:75]
	v_mfma_f32_16x16x32_f16 v[124:127], v[132:135], v[148:151], v[124:127]
	v_mfma_f32_16x16x32_f16 v[120:123], v[140:143], v[148:151], v[120:123]
	v_mfma_f32_16x16x32_f16 v[108:111], v[132:135], v[156:159], v[108:111]
	v_mfma_f32_16x16x32_f16 v[104:107], v[140:143], v[156:159], v[104:107]
	v_mfma_f32_16x16x32_f16 v[92:95], v[132:135], v[164:167], v[92:95]
	v_mfma_f32_16x16x32_f16 v[88:91], v[140:143], v[164:167], v[88:91]
	v_mfma_f32_16x16x32_f16 v[76:79], v[132:135], v[172:175], v[76:79]
	v_mfma_f32_16x16x32_f16 v[72:75], v[140:143], v[172:175], v[72:75]
	s_barrier
	ds_read_b128 v[176:179], v248
	ds_read_b128 v[180:183], v248 offset:1024
	ds_read_b128 v[184:187], v248 offset:2048
	s_add_i32 m0, s31, 0x18000
	ds_read_b128 v[188:191], v248 offset:3072
	global_load_lds_dwordx4 v206, s[86:87]
	s_add_i32 m0, s31, 0x1a000
	s_nop 0
	global_load_lds_dwordx4 v210, s[86:87]
	s_barrier
; #define PG8_STAGE(bufoff, gbase, voff) do { _Pragma("unroll") for (int _i = 0; _i < 2; ++_i) \
;         __builtin_amdgcn_global_load_lds((const unsigned*)((const char*)(gbase) + (voff)[_i]), (LAS unsigned*)(lds + (bufoff) + ldsw + _i * 8192), 16, 0, 0); } while (0)
; #define PG8_LDA(dst, b, h) do { _Pragma("unroll") for (int m = 0; m < 4; ++m) _Pragma("unroll") for (int k = 0; k < 2; ++k) dst[m][k] = *(const LAS h16x8*)(lds + PG8_SA(b, h) + aoff + m * 2048 + k * 1024); } while (0)
; #define PG8_MMA(ai, bj, At, Bt) do { __builtin_amdgcn_s_setprio(1); _Pragma("unroll") for (int m = 0; m < 4; ++m) _Pragma("unroll") for (int n = 0; n < 2; ++n) _Pragma("unroll") for (int k = 0; k < 2; ++k) \
;         acc[ai][bj][m][n] = __builtin_amdgcn_mfma_f32_16x16x32_f16(Bt[n][k], At[m][k], acc[ai][bj][m][n], 0, 0, 0); __builtin_amdgcn_s_setprio(0); } while (0)
; #define PG8_WAIT_V(n) asm volatile("s_waitcnt vmcnt(" #n ")" ::: "memory")
; #define PG8_WAIT_L(n) asm volatile("s_waitcnt lgkmcnt(" #n ")" ::: "memory")
; #define PG8_BAR __builtin_amdgcn_s_barrier()
; #define PG8_SCHED __builtin_amdgcn_sched_barrier(0)
; __device__ __forceinline__ void gemm_phase(LAS unsigned char* lds, const Gemm g, const StaticOrder& S, const Epi& E) {
;     ...
;             PG8_LDA(At, 1, 1); PG8_STAGE(PG8_SA(1, 0), a3, voffA);
;             PG8_BAR; PG8_WAIT_L(0); PG8_MMA(1, 0, At, B0); PG8_BAR; PG8_SCHED;
;             PG8_STAGE(PG8_SB(1, 1), b3 + hstepB, voffB);
;             PG8_WAIT_V(6); PG8_BAR; PG8_MMA(1, 1, At, B1); PG8_BAR;
	s_waitcnt lgkmcnt(0)
	s_waitcnt lgkmcnt(0)
	v_mfma_f32_16x16x32_f16 v[116:119], v[176:179], v[144:147], v[116:119]
	v_mfma_f32_16x16x32_f16 v[112:115], v[184:187], v[144:147], v[112:115]
	v_mfma_f32_16x16x32_f16 v[100:103], v[176:179], v[152:155], v[100:103]
	v_mfma_f32_16x16x32_f16 v[96:99], v[184:187], v[152:155], v[96:99]
	v_mfma_f32_16x16x32_f16 v[84:87], v[176:179], v[160:163], v[84:87]
	v_mfma_f32_16x16x32_f16 v[80:83], v[184:187], v[160:163], v[80:83]
	v_mfma_f32_16x16x32_f16 v[68:71], v[176:179], v[168:171], v[68:71]
	v_mfma_f32_16x16x32_f16 v[64:67], v[184:187], v[168:171], v[64:67]
	v_mfma_f32_16x16x32_f16 v[116:119], v[180:183], v[148:151], v[116:119]
	v_mfma_f32_16x16x32_f16 v[112:115], v[188:191], v[148:151], v[112:115]
	v_mfma_f32_16x16x32_f16 v[100:103], v[180:183], v[156:159], v[100:103]
	v_mfma_f32_16x16x32_f16 v[96:99], v[188:191], v[156:159], v[96:99]
	v_mfma_f32_16x16x32_f16 v[84:87], v[180:183], v[164:167], v[84:87]
	v_mfma_f32_16x16x32_f16 v[80:83], v[188:191], v[164:167], v[80:83]
	v_mfma_f32_16x16x32_f16 v[68:71], v[180:183], v[172:175], v[68:71]
	v_mfma_f32_16x16x32_f16 v[64:67], v[188:191], v[172:175], v[64:67]
	s_mov_b32 m0, s62
	s_barrier
	ds_read_b128 v[144:147], v239 offset:49152
	ds_read_b128 v[148:151], v239 offset:50176
	ds_read_b128 v[152:155], v239 offset:51200
	ds_read_b128 v[156:159], v239 offset:52224
	ds_read_b128 v[160:163], v239 offset:53248
	ds_read_b128 v[164:167], v239 offset:54272
	ds_read_b128 v[168:171], v239 offset:55296
	ds_read_b128 v[172:175], v239 offset:56320
	global_load_lds_dwordx4 v204, s[88:89]
	s_mov_b32 m0, s63
	s_nop 0
	global_load_lds_dwordx4 v208, s[88:89]
	s_barrier
	s_waitcnt lgkmcnt(0)
	s_waitcnt lgkmcnt(0)
	v_mfma_f32_16x16x32_f16 v[60:63], v[128:131], v[144:147], v[60:63]
	v_mfma_f32_16x16x32_f16 v[56:59], v[136:139], v[144:147], v[56:59]
	v_mfma_f32_16x16x32_f16 v[44:47], v[128:131], v[152:155], v[44:47]
	v_mfma_f32_16x16x32_f16 v[40:43], v[136:139], v[152:155], v[40:43]
	v_mfma_f32_16x16x32_f16 v[28:31], v[128:131], v[160:163], v[28:31]
	v_mfma_f32_16x16x32_f16 v[24:27], v[136:139], v[160:163], v[24:27]
	v_mfma_f32_16x16x32_f16 v[12:15], v[128:131], v[168:171], v[12:15]
	v_mfma_f32_16x16x32_f16 v[8:11], v[136:139], v[168:171], v[8:11]
	v_mfma_f32_16x16x32_f16 v[60:63], v[132:135], v[148:151], v[60:63]
	v_mfma_f32_16x16x32_f16 v[56:59], v[140:143], v[148:151], v[56:59]
	v_mfma_f32_16x16x32_f16 v[44:47], v[132:135], v[156:159], v[44:47]
	v_mfma_f32_16x16x32_f16 v[40:43], v[140:143], v[156:159], v[40:43]
	v_mfma_f32_16x16x32_f16 v[28:31], v[132:135], v[164:167], v[28:31]
	v_mfma_f32_16x16x32_f16 v[24:27], v[140:143], v[164:167], v[24:27]
	v_mfma_f32_16x16x32_f16 v[12:15], v[132:135], v[172:175], v[12:15]
	v_mfma_f32_16x16x32_f16 v[8:11], v[140:143], v[172:175], v[8:11]
	s_barrier
	s_add_i32 m0, s31, 0x1c000
	s_nop 0
	global_load_lds_dwordx4 v206, s[96:97]
	s_add_i32 m0, s31, 0x1e000
	s_nop 0
	global_load_lds_dwordx4 v210, s[96:97]
	s_waitcnt vmcnt(6)
	s_barrier
	v_mfma_f32_16x16x32_f16 v[52:55], v[176:179], v[144:147], v[52:55]
	v_mfma_f32_16x16x32_f16 v[48:51], v[184:187], v[144:147], v[48:51]
	v_mfma_f32_16x16x32_f16 v[36:39], v[176:179], v[152:155], v[36:39]
	v_mfma_f32_16x16x32_f16 v[32:35], v[184:187], v[152:155], v[32:35]
	v_mfma_f32_16x16x32_f16 v[20:23], v[176:179], v[160:163], v[20:23]
	v_mfma_f32_16x16x32_f16 v[16:19], v[184:187], v[160:163], v[16:19]
	v_mfma_f32_16x16x32_f16 v[4:7], v[176:179], v[168:171], v[4:7]
	v_mfma_f32_16x16x32_f16 v[0:3], v[184:187], v[168:171], v[0:3]
	v_mfma_f32_16x16x32_f16 v[52:55], v[180:183], v[148:151], v[52:55]
	v_mfma_f32_16x16x32_f16 v[48:51], v[188:191], v[148:151], v[48:51]
	v_mfma_f32_16x16x32_f16 v[36:39], v[180:183], v[156:159], v[36:39]
	v_mfma_f32_16x16x32_f16 v[32:35], v[188:191], v[156:159], v[32:35]
	v_mfma_f32_16x16x32_f16 v[20:23], v[180:183], v[164:167], v[20:23]
	v_mfma_f32_16x16x32_f16 v[16:19], v[188:191], v[164:167], v[16:19]
	v_mfma_f32_16x16x32_f16 v[4:7], v[180:183], v[172:175], v[4:7]
	v_mfma_f32_16x16x32_f16 v[0:3], v[188:191], v[172:175], v[0:3]
	s_add_u32 s0, s0, 0x100
	s_addc_u32 s1, s1, 0
	s_add_u32 s27, s27, 0x100
	s_addc_u32 s33, s33, 0
	s_cmp_ge_u32 s38, s64
	s_mov_b32 s34, s38
	s_barrier
	s_cbranch_scc0 .LBB0_762
	s_setprio 0
	s_lshl_b32 s0, s84, 8
	s_or_b32 s27, s0, s65
	v_lshl_add_u32 v240, s30, 8, v200
	v_or_b32_e32 v216, s27, v202
	s_cmp_eq_u32 s93, 3
	s_cbranch_scc1 .Lst16_fast
	s_cmp_eq_u32 s93, 1
	s_cbranch_scc0 .Llora_no
	s_lshr_b32 s0, s84, 2
	s_cmp_lt_u32 s0, 2
	s_cbranch_scc1 .Llora_fast
